# ret_out unit epilogue chunks 1-7 hand-written: gate/gain loads batched up front, silu via v_rcp_f32 (f32), no per-chunk vmcnt(0) round trips
# baseline (speedup 1.0000x reference)
.LBB0_490:
	s_or_b64 exec, exec, s[0:1]
	v_lshlrev_b32_e32 v70, 7, v6
	v_lshlrev_b32_e32 v2, 3, v5
	v_ashrrev_i32_e32 v71, 31, v70
	v_and_b32_e32 v7, 56, v2
	v_bfe_u32 v13, v5, 3, 5
	v_lshlrev_b64 v[72:73], 1, v[70:71]
	v_lshlrev_b32_e32 v0, 3, v7
	v_mov_b32_e32 v1, v65
	v_or_b32_e32 v8, v3, v13
	v_lshl_add_u64 v[0:1], s[40:41], 0, v[0:1]
	v_lshlrev_b32_e32 v8, 9, v8
	v_mov_b32_e32 v9, v65
	v_lshl_add_u64 v[18:19], s[38:39], 0, v[72:73]
	v_lshlrev_b32_e32 v64, 1, v7
	v_lshl_add_u64 v[38:39], v[0:1], 0, v[8:9]
	v_lshl_add_u64 v[42:43], v[18:19], 0, v[64:65]
	v_add_u32_e32 v7, v68, v13
	flat_load_dwordx4 v[8:11], v[38:39]
	flat_load_dwordx4 v[14:17], v[38:39] offset:16
	flat_load_dwordx4 v[18:21], v[38:39] offset:32
	v_mad_i64_i32 v[34:35], s[0:1], v7, s57, v[42:43]
	flat_load_dwordx4 v[22:25], v[34:35]
	flat_load_dwordx4 v[26:29], v[34:35] offset:128
	flat_load_dwordx4 v[30:33], v[34:35] offset:1536
	s_nop 0
	flat_load_dwordx4 v[34:37], v[34:35] offset:1664
	s_nop 0
	flat_load_dwordx4 v[38:41], v[38:39] offset:48
	v_or_b32_sdwa v140, v5, s61 dst_sel:DWORD dst_unused:UNUSED_PAD src0_sel:BYTE_0 src1_sel:DWORD
	v_lshrrev_b32_e32 v141, 3, v140
	v_add_u32_e32 v142, v68, v141
	v_mad_i64_i32 v[134:135], s[0:1], v142, s57, v[42:43]
	v_or_b32_e32 v143, v3, v141
	v_lshlrev_b32_e32 v136, 9, v143
	v_mov_b32_e32 v137, v65
	v_lshl_add_u64 v[136:137], v[0:1], 0, v[136:137]
	global_load_dwordx4 v[160:163], v[134:135], off
	global_load_dwordx4 v[164:167], v[134:135], off offset:128
	global_load_dwordx4 v[168:171], v[134:135], off offset:1536
	global_load_dwordx4 v[172:175], v[134:135], off offset:1664
	global_load_dwordx4 v[176:179], v[136:137], off
	global_load_dwordx4 v[180:183], v[136:137], off offset:16
	global_load_dwordx4 v[184:187], v[136:137], off offset:32
	global_load_dwordx4 v[188:191], v[136:137], off offset:48
	v_bfe_u32 v140, v5, 4, 4
	v_add_u32_e32 v140, v68, v140
	v_mad_i64_i32 v[138:139], s[0:1], v140, s57, v[66:67]
	v_lshl_add_u64 v[138:139], v[138:139], 0, v[72:73]
	v_lshlrev_b32_e32 v140, 3, v5
	v_and_b32_e32 v140, 0x78, v140
	v_lshlrev_b32_e32 v140, 1, v140
	v_mov_b32_e32 v141, v65
	v_lshl_add_u64 v[138:139], v[138:139], 0, v[140:141]
	v_mov_b32_e32 v140, 0x1a000
	global_load_dwordx4 v[192:195], v[138:139], off offset:3072
	v_lshl_add_u64 v[138:139], v[138:139], 0, v[140:141]
	global_load_dwordx4 v[196:199], v[138:139], off offset:3072
	v_lshl_add_u64 v[138:139], v[138:139], 0, v[140:141]
	global_load_dwordx4 v[200:203], v[138:139], off offset:3072
	v_lshl_add_u64 v[138:139], v[138:139], 0, v[140:141]
	global_load_dwordx4 v[204:207], v[138:139], off offset:3072
	v_mul_u32_u24_e32 v7, 0x88, v13
	v_mad_i32_i24 v4, v4, s52, 0
	v_lshlrev_b32_e32 v7, 1, v7
	v_add3_u32 v7, v4, v7, v64
	s_add_i32 s2, s2, s84
	s_waitcnt vmcnt(12) lgkmcnt(0)
	v_mov_b32_e32 v44, v8
	v_mov_b32_e32 v45, v10
	v_mov_b32_e32 v10, v9
	v_mov_b32_e32 v8, v14
	v_mov_b32_e32 v9, v16
	v_mov_b32_e32 v16, v15
	v_mov_b32_e32 v14, v18
	v_mov_b32_e32 v15, v20
	v_mov_b32_e32 v20, v19
	v_lshlrev_b32_e32 v18, 16, v22
	v_and_b32_e32 v19, 0xffff0000, v22
	v_lshlrev_b32_e32 v22, 16, v23
	v_and_b32_e32 v23, 0xffff0000, v23
	v_lshlrev_b32_e32 v48, 16, v26
	v_and_b32_e32 v49, 0xffff0000, v26
	v_lshlrev_b32_e32 v26, 16, v27
	v_and_b32_e32 v27, 0xffff0000, v27
	v_lshlrev_b32_e32 v52, 16, v30
	v_and_b32_e32 v53, 0xffff0000, v30
	v_lshlrev_b32_e32 v30, 16, v31
	v_and_b32_e32 v31, 0xffff0000, v31
	v_lshlrev_b32_e32 v56, 16, v34
	v_and_b32_e32 v57, 0xffff0000, v34
	v_lshlrev_b32_e32 v34, 16, v35
	v_and_b32_e32 v35, 0xffff0000, v35
	v_pk_mul_f32 v[76:77], v[16:17], v[26:27]
	v_pk_mul_f32 v[84:85], v[16:17], v[22:23]
	v_pk_mul_f32 v[86:87], v[16:17], v[34:35]
	v_pk_mul_f32 v[16:17], v[16:17], v[30:31]
	v_lshlrev_b32_e32 v46, 16, v24
	v_and_b32_e32 v47, 0xffff0000, v24
	v_lshlrev_b32_e32 v50, 16, v28
	v_and_b32_e32 v51, 0xffff0000, v28
	v_pk_mul_f32 v[60:61], v[10:11], v[48:49]
	v_pk_mul_f32 v[62:63], v[10:11], v[18:19]
	v_pk_mul_f32 v[74:75], v[10:11], v[56:57]
	v_pk_mul_f32 v[10:11], v[10:11], v[52:53]
	v_pk_fma_f32 v[22:23], v[8:9], v[22:23], v[76:77] neg_lo:[0,0,1] neg_hi:[0,0,1]
	v_pk_fma_f32 v[26:27], v[8:9], v[26:27], v[84:85]
	v_pk_fma_f32 v[30:31], v[8:9], v[30:31], v[86:87] neg_lo:[0,0,1] neg_hi:[0,0,1]
	v_pk_fma_f32 v[8:9], v[8:9], v[34:35], v[16:17]
	v_lshlrev_b32_e32 v58, 16, v36
	v_and_b32_e32 v59, 0xffff0000, v36
	v_pk_mul_f32 v[88:89], v[20:21], v[50:51]
	v_pk_fma_f32 v[18:19], v[44:45], v[18:19], v[60:61] neg_lo:[0,0,1] neg_hi:[0,0,1]
	v_pk_fma_f32 v[48:49], v[44:45], v[48:49], v[62:63]
	v_pk_fma_f32 v[52:53], v[44:45], v[52:53], v[74:75] neg_lo:[0,0,1] neg_hi:[0,0,1]
	v_pk_fma_f32 v[10:11], v[44:45], v[56:57], v[10:11]
	v_pk_mul_f32 v[44:45], v[8:9], s[44:45] op_sel_hi:[1,0]
	v_pk_mul_f32 v[8:9], v[20:21], v[46:47]
	v_lshlrev_b32_e32 v54, 16, v32
	v_and_b32_e32 v55, 0xffff0000, v32
	v_pk_mul_f32 v[34:35], v[10:11], s[44:45] op_sel_hi:[1,0]
	v_pk_fma_f32 v[10:11], v[14:15], v[46:47], v[88:89] neg_lo:[0,0,1] neg_hi:[0,0,1]
	v_pk_fma_f32 v[46:47], v[14:15], v[50:51], v[8:9]
	v_pk_mul_f32 v[8:9], v[20:21], v[58:59]
	v_lshlrev_b32_e32 v28, 16, v29
	v_pk_fma_f32 v[8:9], v[14:15], v[54:55], v[8:9] neg_lo:[0,0,1] neg_hi:[0,0,1]
	v_and_b32_e32 v29, 0xffff0000, v29
	v_pk_mul_f32 v[50:51], v[8:9], s[44:45] op_sel_hi:[1,0]
	v_pk_mul_f32 v[8:9], v[20:21], v[54:55]
	v_lshlrev_b32_e32 v24, 16, v25
	v_pk_fma_f32 v[8:9], v[14:15], v[58:59], v[8:9]
	v_and_b32_e32 v25, 0xffff0000, v25
	v_pk_mul_f32 v[14:15], v[8:9], s[44:45] op_sel_hi:[1,0]
	v_mov_b32_e32 v9, v40
	v_mov_b32_e32 v40, v39
	v_mov_b32_e32 v8, v38
	v_pk_mul_f32 v[20:21], v[40:41], v[28:29]
	v_lshlrev_b32_e32 v36, 16, v37
	v_and_b32_e32 v37, 0xffff0000, v37
	v_pk_fma_f32 v[20:21], v[8:9], v[24:25], v[20:21] neg_lo:[0,0,1] neg_hi:[0,0,1]
	v_pk_mul_f32 v[24:25], v[40:41], v[24:25]
	v_lshlrev_b32_e32 v32, 16, v33
	v_and_b32_e32 v33, 0xffff0000, v33
	v_pk_fma_f32 v[24:25], v[8:9], v[28:29], v[24:25]
	v_pk_mul_f32 v[28:29], v[40:41], v[36:37]
	v_cvt_pk_bf16_f32 v10, v10, v11
	v_pk_fma_f32 v[28:29], v[8:9], v[32:33], v[28:29] neg_lo:[0,0,1] neg_hi:[0,0,1]
	v_pk_mul_f32 v[32:33], v[40:41], v[32:33]
	v_cvt_pk_bf16_f32 v11, v20, v21
	v_pk_fma_f32 v[8:9], v[8:9], v[36:37], v[32:33]
	v_pk_mul_f32 v[16:17], v[52:53], s[44:45] op_sel_hi:[1,0]
	v_pk_mul_f32 v[32:33], v[8:9], s[44:45] op_sel_hi:[1,0]
	v_cvt_pk_bf16_f32 v8, v18, v19
	v_cvt_pk_bf16_f32 v9, v22, v23
	v_pk_mul_f32 v[30:31], v[30:31], s[44:45] op_sel_hi:[1,0]
	v_pk_mul_f32 v[28:29], v[28:29], s[44:45] op_sel_hi:[1,0]
	ds_write_b128 v7, v[8:11]
	v_cvt_pk_bf16_f32 v8, v48, v49
	v_cvt_pk_bf16_f32 v9, v26, v27
	v_cvt_pk_bf16_f32 v10, v46, v47
	v_cvt_pk_bf16_f32 v11, v24, v25
	ds_write_b128 v7, v[8:11] offset:128
	v_cvt_pk_bf16_f32 v8, v16, v17
	v_cvt_pk_bf16_f32 v9, v30, v31
	v_cvt_pk_bf16_f32 v10, v50, v51
	v_cvt_pk_bf16_f32 v11, v28, v29
	ds_write_b128 v7, v[8:11] offset:17408
	v_cvt_pk_bf16_f32 v8, v34, v35
	v_cvt_pk_bf16_f32 v9, v44, v45
	v_cvt_pk_bf16_f32 v10, v14, v15
	v_cvt_pk_bf16_f32 v11, v32, v33
	ds_write_b128 v7, v[8:11] offset:17536
	v_or_b32_sdwa v7, v5, s61 dst_sel:DWORD dst_unused:UNUSED_PAD src0_sel:BYTE_0 src1_sel:DWORD
	v_lshrrev_b32_e32 v13, 3, v7
	v_add_u32_e32 v8, v68, v13
	v_or_b32_e32 v3, v3, v13
	v_mad_i64_i32 v[22:23], s[0:1], v8, s57, v[42:43]
	v_lshlrev_b32_e32 v26, 9, v3
	v_mov_b32_e32 v27, v65
	s_nop 0
	v_lshl_add_u64 v[0:1], v[0:1], 0, v[26:27]
	v_mul_u32_u24_e32 v3, 0x88, v13
	v_lshlrev_b32_e32 v3, 1, v3
	v_add3_u32 v3, v4, v3, v64
	v_lshrrev_b32_e32 v7, 4, v7
	s_waitcnt vmcnt(4) lgkmcnt(0)
	v_mov_b64_e32 v[8:9], v[160:161]
	v_mov_b64_e32 v[10:11], v[162:163]
	v_mov_b64_e32 v[14:15], v[164:165]
	v_mov_b64_e32 v[16:17], v[166:167]
	v_mov_b64_e32 v[18:19], v[168:169]
	v_mov_b64_e32 v[20:21], v[170:171]
	v_mov_b64_e32 v[22:23], v[172:173]
	v_mov_b64_e32 v[24:25], v[174:175]
	v_mov_b64_e32 v[26:27], v[176:177]
	v_mov_b64_e32 v[28:29], v[178:179]
	v_mov_b64_e32 v[30:31], v[180:181]
	v_mov_b64_e32 v[32:33], v[182:183]
	v_mov_b64_e32 v[34:35], v[184:185]
	v_mov_b64_e32 v[36:37], v[186:187]
	v_mov_b64_e32 v[38:39], v[188:189]
	v_mov_b64_e32 v[40:41], v[190:191]
	v_lshlrev_b32_e32 v0, 16, v8
	v_lshlrev_b32_e32 v44, 16, v14
	v_and_b32_e32 v45, 0xffff0000, v14
	v_mov_b32_e32 v57, v28
	v_mov_b32_e32 v28, v27
	v_and_b32_e32 v1, 0xffff0000, v8
	v_mov_b32_e32 v56, v26
	v_pk_mul_f32 v[26:27], v[28:29], v[44:45]
	v_lshlrev_b32_e32 v52, 16, v22
	v_and_b32_e32 v53, 0xffff0000, v22
	v_pk_fma_f32 v[26:27], v[56:57], v[0:1], v[26:27] neg_lo:[0,0,1] neg_hi:[0,0,1]
	v_pk_mul_f32 v[0:1], v[28:29], v[0:1]
	v_lshlrev_b32_e32 v48, 16, v18
	v_and_b32_e32 v49, 0xffff0000, v18
	v_pk_fma_f32 v[0:1], v[56:57], v[44:45], v[0:1]
	v_pk_mul_f32 v[44:45], v[28:29], v[52:53]
	v_lshlrev_b32_e32 v14, 16, v15
	v_and_b32_e32 v15, 0xffff0000, v15
	v_pk_fma_f32 v[44:45], v[56:57], v[48:49], v[44:45] neg_lo:[0,0,1] neg_hi:[0,0,1]
	v_pk_mul_f32 v[28:29], v[28:29], v[48:49]
	v_mov_b32_e32 v49, v32
	v_mov_b32_e32 v32, v31
	v_lshlrev_b32_e32 v8, 16, v9
	v_and_b32_e32 v9, 0xffff0000, v9
	v_mov_b32_e32 v48, v30
	v_pk_mul_f32 v[30:31], v[32:33], v[14:15]
	v_lshlrev_b32_e32 v22, 16, v23
	v_and_b32_e32 v23, 0xffff0000, v23
	v_pk_fma_f32 v[30:31], v[48:49], v[8:9], v[30:31] neg_lo:[0,0,1] neg_hi:[0,0,1]
	v_pk_mul_f32 v[8:9], v[32:33], v[8:9]
	v_lshlrev_b32_e32 v18, 16, v19
	v_and_b32_e32 v19, 0xffff0000, v19
	v_pk_fma_f32 v[14:15], v[48:49], v[14:15], v[8:9]
	v_pk_mul_f32 v[8:9], v[32:33], v[22:23]
	v_pk_fma_f32 v[28:29], v[56:57], v[52:53], v[28:29]
	v_pk_fma_f32 v[8:9], v[48:49], v[18:19], v[8:9] neg_lo:[0,0,1] neg_hi:[0,0,1]
	v_lshlrev_b32_e32 v42, 16, v10
	v_pk_mul_f32 v[52:53], v[8:9], s[44:45] op_sel_hi:[1,0]
	v_pk_mul_f32 v[8:9], v[32:33], v[18:19]
	v_and_b32_e32 v43, 0xffff0000, v10
	v_pk_fma_f32 v[8:9], v[48:49], v[22:23], v[8:9]
	v_lshlrev_b32_e32 v46, 16, v16
	v_and_b32_e32 v47, 0xffff0000, v16
	v_lshlrev_b32_e32 v50, 16, v20
	v_and_b32_e32 v51, 0xffff0000, v20
	v_lshlrev_b32_e32 v54, 16, v24
	v_and_b32_e32 v55, 0xffff0000, v24
	v_pk_mul_f32 v[18:19], v[8:9], s[44:45] op_sel_hi:[1,0]
	v_mov_b32_e32 v9, v36
	v_mov_b32_e32 v36, v35
	v_mov_b32_e32 v8, v34
	v_pk_mul_f32 v[22:23], v[36:37], v[46:47]
	v_pk_mul_f32 v[32:33], v[36:37], v[42:43]
	v_pk_mul_f32 v[34:35], v[36:37], v[54:55]
	v_pk_mul_f32 v[36:37], v[36:37], v[50:51]
	v_pk_fma_f32 v[22:23], v[8:9], v[42:43], v[22:23] neg_lo:[0,0,1] neg_hi:[0,0,1]
	v_pk_fma_f32 v[32:33], v[8:9], v[46:47], v[32:33]
	v_pk_fma_f32 v[34:35], v[8:9], v[50:51], v[34:35] neg_lo:[0,0,1] neg_hi:[0,0,1]
	v_pk_fma_f32 v[8:9], v[8:9], v[54:55], v[36:37]
	v_lshlrev_b32_e32 v16, 16, v17
	v_and_b32_e32 v17, 0xffff0000, v17
	v_pk_mul_f32 v[36:37], v[8:9], s[44:45] op_sel_hi:[1,0]
	v_mov_b32_e32 v9, v40
	v_mov_b32_e32 v40, v39
	v_lshlrev_b32_e32 v10, 16, v11
	v_and_b32_e32 v11, 0xffff0000, v11
	v_mov_b32_e32 v8, v38
	v_pk_mul_f32 v[38:39], v[40:41], v[16:17]
	v_lshlrev_b32_e32 v24, 16, v25
	v_and_b32_e32 v25, 0xffff0000, v25
	v_pk_fma_f32 v[38:39], v[8:9], v[10:11], v[38:39] neg_lo:[0,0,1] neg_hi:[0,0,1]
	v_pk_mul_f32 v[10:11], v[40:41], v[10:11]
	v_lshlrev_b32_e32 v20, 16, v21
	v_and_b32_e32 v21, 0xffff0000, v21
	v_pk_fma_f32 v[16:17], v[8:9], v[16:17], v[10:11]
	v_pk_mul_f32 v[10:11], v[40:41], v[24:25]
	v_pk_mul_f32 v[44:45], v[44:45], s[44:45] op_sel_hi:[1,0]
	v_pk_fma_f32 v[10:11], v[8:9], v[20:21], v[10:11] neg_lo:[0,0,1] neg_hi:[0,0,1]
	v_pk_mul_f32 v[34:35], v[34:35], s[44:45] op_sel_hi:[1,0]
	v_pk_mul_f32 v[42:43], v[10:11], s[44:45] op_sel_hi:[1,0]
	v_pk_mul_f32 v[10:11], v[40:41], v[20:21]
	v_pk_mul_f32 v[28:29], v[28:29], s[44:45] op_sel_hi:[1,0]
	v_pk_fma_f32 v[8:9], v[8:9], v[24:25], v[10:11]
	v_cvt_pk_bf16_f32 v10, v22, v23
	v_pk_mul_f32 v[20:21], v[8:9], s[44:45] op_sel_hi:[1,0]
	v_cvt_pk_bf16_f32 v8, v26, v27
	v_cvt_pk_bf16_f32 v9, v30, v31
	v_cvt_pk_bf16_f32 v11, v38, v39
	ds_write_b128 v3, v[8:11]
	v_cvt_pk_bf16_f32 v8, v0, v1
	v_cvt_pk_bf16_f32 v9, v14, v15
	v_cvt_pk_bf16_f32 v10, v32, v33
	v_cvt_pk_bf16_f32 v11, v16, v17
	ds_write_b128 v3, v[8:11] offset:128
	v_cvt_pk_bf16_f32 v8, v44, v45
	v_cvt_pk_bf16_f32 v9, v52, v53
	v_cvt_pk_bf16_f32 v10, v34, v35
	v_cvt_pk_bf16_f32 v11, v42, v43
	ds_write_b128 v3, v[8:11] offset:17408
	v_cvt_pk_bf16_f32 v8, v28, v29
	v_cvt_pk_bf16_f32 v9, v18, v19
	v_cvt_pk_bf16_f32 v10, v36, v37
	v_cvt_pk_bf16_f32 v11, v20, v21
	ds_write_b128 v3, v[8:11] offset:17536
	v_bfe_u32 v9, v5, 4, 4
	v_add_u32_e32 v10, v68, v9
	v_and_b32_e32 v8, 0x78, v2
	v_mad_i64_i32 v[0:1], s[0:1], v10, s57, v[66:67]
	v_lshl_add_u64 v[0:1], v[0:1], 0, v[72:73]
	v_lshlrev_b32_e32 v64, 1, v8
	v_lshl_add_u64 v[0:1], v[0:1], 0, v[64:65]
	v_mul_u32_u24_e32 v8, 0x48, v8
	v_lshlrev_b32_e32 v11, 1, v8
	v_lshlrev_b32_e32 v9, 1, v9
	v_add_u32_e32 v14, v4, v11
	v_add3_u32 v13, v4, v9, v11
	v_add_u32_e32 v15, v14, v9
	v_add_u32_e32 v8, 32, v10
	v_mad_i64_i32 v[8:9], s[0:1], v8, s57, v[66:67]
	v_lshl_add_u64 v[8:9], v[8:9], 0, v[72:73]
	v_lshl_add_u64 v[8:9], v[8:9], 0, v[64:65]
	v_and_b32_e32 v20, 15, v5
	v_bfe_u32 v21, v5, 4, 2
	v_lshrrev_b32_e32 v5, 2, v5
	v_and_or_b32 v76, v5, 48, v20
	v_lshlrev_b32_e32 v5, 2, v21
	v_lshlrev_b32_e32 v74, 4, v21
	v_sub_u32_e32 v69, v76, v5
	v_add_u32_e32 v16, -2, v69
	v_cvt_f32_i32_e32 v16, v16
	v_add_u32_e32 v17, -3, v69
	v_subrev_u32_e32 v22, 17, v69
	v_subrev_u32_e32 v23, 18, v69
	v_subrev_u32_e32 v24, 19, v69
	v_subrev_u32_e32 v25, 33, v69
	v_cvt_f32_i32_e32 v17, v17
	v_cvt_f32_i32_e32 v22, v22
	v_cvt_f32_i32_e32 v23, v23
	v_cvt_f32_i32_e32 v24, v24
	v_cvt_f32_i32_e32 v25, v25
	v_subrev_u32_e32 v26, 34, v69
	v_subrev_u32_e32 v27, 35, v69
	v_cvt_f32_i32_e32 v26, v26
	v_cvt_f32_i32_e32 v34, v27
	v_subrev_u32_e32 v28, 49, v69
	s_add_i32 s45, s45, s48
	s_cmpk_gt_i32 s2, 0x62f
	s_waitcnt vmcnt(3) lgkmcnt(0)
	v_mov_b64_e32 v[0:1], v[192:193]
	v_mov_b64_e32 v[2:3], v[194:195]
	ds_write_b16 v13, v0 offset:34816
	ds_write_b16_d16_hi v15, v0 offset:34960
	ds_write_b16 v13, v1 offset:35104
	ds_write_b16_d16_hi v15, v1 offset:35248
	ds_write_b16 v13, v2 offset:35392
	ds_write_b16_d16_hi v15, v2 offset:35536
	ds_write_b16 v13, v3 offset:35680
	ds_write_b16_d16_hi v15, v3 offset:35824
	v_add_u32_e32 v0, v68, v7
	v_mad_i64_i32 v[0:1], s[0:1], v0, s57, v[66:67]
	v_lshl_add_u64 v[0:1], v[0:1], 0, v[72:73]
	v_lshl_add_u64 v[0:1], v[0:1], 0, v[64:65]
	v_lshlrev_b32_e32 v7, 1, v7
	v_add3_u32 v11, v4, v7, v11
	v_add_u32_e32 v7, v14, v7
	s_waitcnt vmcnt(2) lgkmcnt(0)
	v_mov_b64_e32 v[0:1], v[196:197]
	v_mov_b64_e32 v[2:3], v[198:199]
	ds_write_b16 v11, v0 offset:34816
	ds_write_b16_d16_hi v7, v0 offset:34960
	ds_write_b16 v11, v1 offset:35104
	ds_write_b16_d16_hi v7, v1 offset:35248
	ds_write_b16 v11, v2 offset:35392
	ds_write_b16_d16_hi v7, v2 offset:35536
	ds_write_b16 v11, v3 offset:35680
	ds_write_b16_d16_hi v7, v3 offset:35824
	v_cvt_f32_i32_e32 v8, v6
	v_add_u32_e32 v6, 48, v10
	v_mad_i64_i32 v[6:7], s[0:1], v6, s57, v[66:67]
	v_lshl_add_u64 v[6:7], v[6:7], 0, v[72:73]
	v_lshl_add_u64 v[6:7], v[6:7], 0, v[64:65]
	s_waitcnt vmcnt(1) lgkmcnt(0)
	v_mov_b64_e32 v[0:1], v[200:201]
	v_mov_b64_e32 v[2:3], v[202:203]
	ds_write_b16 v13, v0 offset:34880
	ds_write_b16_d16_hi v15, v0 offset:35024
	ds_write_b16 v13, v1 offset:35168
	ds_write_b16_d16_hi v15, v1 offset:35312
	ds_write_b16 v13, v2 offset:35456
	ds_write_b16_d16_hi v15, v2 offset:35600
	ds_write_b16 v13, v3 offset:35744
	ds_write_b16_d16_hi v15, v3 offset:35888
	v_sub_f32_e32 v8, 0xc0a00000, v8
	v_cmp_gt_f32_e32 vcc, s53, v8
	v_add_u32_e32 v9, v4, v74
	v_xad_u32 v10, v5, -1, v76
	v_cndmask_b32_e32 v29, 0, v78, vcc
	v_add_f32_e32 v8, v8, v29
	v_exp_f32_e32 v6, v8
	v_cndmask_b32_e32 v7, 0, v79, vcc
	v_mad_u32_u24 v18, v76, s62, v9
	v_mad_u32_u24 v19, v20, s62, v9
	v_ldexp_f32 v6, v6, v7
	v_sub_f32_e32 v6, 1.0, v6
	v_cmp_gt_f32_e32 vcc, s54, v6
	v_cvt_f32_i32_e32 v9, v69
	v_cvt_f32_i32_e32 v10, v10
	v_cndmask_b32_e64 v7, 0, 32, vcc
	v_ldexp_f32 v6, v6, v7
	v_log_f32_e32 v6, v6
	v_cndmask_b32_e32 v7, 0, v80, vcc
	v_or_b32_e32 v14, 32, v5
	s_waitcnt vmcnt(0) lgkmcnt(0)
	v_mov_b64_e32 v[0:1], v[204:205]
	v_mov_b64_e32 v[2:3], v[206:207]
	ds_write_b16 v13, v0 offset:34912
	ds_write_b16_d16_hi v15, v0 offset:35056
	ds_write_b16 v13, v1 offset:35200
	ds_write_b16_d16_hi v15, v1 offset:35344
	ds_write_b16 v13, v2 offset:35488
	ds_write_b16_d16_hi v15, v2 offset:35632
	ds_write_b16 v13, v3 offset:35776
	ds_write_b16_d16_hi v15, v3 offset:35920
	v_mul_f32_e32 v8, 0x3f317217, v6
	v_fma_f32 v8, v6, s55, -v8
	v_fmac_f32_e32 v8, 0x3377d1cf, v6
	v_fmac_f32_e32 v8, 0x3f317217, v6
	v_cmp_lt_f32_e64 vcc, |v6|, s56
	s_waitcnt lgkmcnt(0)
	s_barrier
	v_cndmask_b32_e32 v6, v6, v8, vcc
	v_sub_f32_e32 v6, v6, v7
	ds_read_b128 v[0:3], v19 offset:17408
	v_sub_u32_e32 v14, v76, v14
	v_mul_f32_e32 v83, 0x3fb8aa3b, v6
	v_cvt_f32_i32_e32 v14, v14
	v_mul_f32_e64 v6, |v9|, v83
	v_mul_f32_e64 v7, |v10|, v83
	v_mul_f32_e64 v8, |v16|, v83
	v_cmp_gt_f32_e32 vcc, s53, v6
	v_cmp_gt_f32_e64 s[0:1], s53, v7
	v_cmp_gt_f32_e64 s[4:5], s53, v8
	v_or_b32_e32 v11, 16, v5
	v_or_b32_e32 v5, 48, v5
	v_cndmask_b32_e32 v6, 0, v78, vcc
	v_cndmask_b32_e64 v7, 0, v78, s[0:1]
	v_cndmask_b32_e64 v8, 0, v78, s[4:5]
	v_sub_u32_e32 v11, v76, v11
	v_sub_u32_e32 v5, v76, v5
	v_fma_f32 v42, |v9|, v83, v6
	v_fma_f32 v10, |v10|, v83, v7
	v_fma_f32 v43, |v16|, v83, v8
	ds_read_b128 v[56:59], v18
	ds_read_b128 v[6:9], v19 offset:21760
	v_cvt_f32_i32_e32 v11, v11
	v_cvt_f32_i32_e32 v5, v5
	v_mul_f32_e64 v27, |v17|, v83
	v_mul_f32_e64 v29, |v22|, v83
	v_mul_f32_e64 v30, |v23|, v83
	v_mul_f32_e64 v31, |v24|, v83
	v_mul_f32_e64 v32, |v14|, v83
	v_mul_f32_e64 v33, |v25|, v83
	v_cmp_gt_f32_e64 s[6:7], s53, v27
	v_cmp_gt_f32_e64 s[10:11], s53, v29
	v_cmp_gt_f32_e64 s[12:13], s53, v30
	v_cmp_gt_f32_e64 s[14:15], s53, v31
	v_cmp_gt_f32_e64 s[16:17], s53, v32
	v_cmp_gt_f32_e64 s[18:19], s53, v33
	v_cndmask_b32_e64 v27, 0, v78, s[6:7]
	v_cndmask_b32_e64 v29, 0, v78, s[10:11]
	v_cndmask_b32_e64 v30, 0, v78, s[12:13]
	v_cndmask_b32_e64 v31, 0, v78, s[14:15]
	v_cndmask_b32_e64 v32, 0, v78, s[16:17]
	v_cndmask_b32_e64 v33, 0, v78, s[18:19]
	v_fma_f32 v44, |v17|, v83, v27
	v_fma_f32 v45, |v22|, v83, v29
	v_fma_f32 v48, |v23|, v83, v30
	v_fma_f32 v49, |v24|, v83, v31
	v_fma_f32 v50, |v14|, v83, v32
	v_fma_f32 v13, |v25|, v83, v33
	ds_read_b128 v[60:63], v18 offset:64
	ds_read_b128 v[14:17], v19 offset:17472
	ds_read_b128 v[22:25], v19 offset:26112
	s_waitcnt lgkmcnt(4)
	v_mfma_f32_16x16x32_bf16 v[0:3], v[0:3], v[56:59], 0
	v_cvt_f32_i32_e32 v64, v28
	v_mul_f32_e64 v28, |v11|, v83
	v_mul_f32_e64 v35, |v26|, v83
	v_mul_f32_e64 v36, |v34|, v83
	v_mul_f32_e64 v37, |v5|, v83
	v_cmp_gt_f32_e64 s[8:9], s53, v28
	v_cmp_gt_f32_e64 s[20:21], s53, v35
	v_cmp_gt_f32_e64 s[22:23], s53, v36
	v_cmp_gt_f32_e64 s[24:25], s53, v37
	v_cndmask_b32_e64 v28, 0, v78, s[8:9]
	v_cndmask_b32_e64 v35, 0, v78, s[20:21]
	v_cndmask_b32_e64 v36, 0, v78, s[22:23]
	v_cndmask_b32_e64 v38, 0, v78, s[24:25]
	v_fma_f32 v11, |v11|, v83, v28
	v_fma_f32 v91, |v26|, v83, v35
	ds_read_b128 v[26:29], v19 offset:21824
	ds_read_b128 v[30:33], v19 offset:30464
	v_fma_f32 v93, |v34|, v83, v36
	ds_read_b128 v[34:37], v19 offset:26176
	v_fma_f32 v5, |v5|, v83, v38
	ds_read_b128 v[38:41], v19 offset:30528
	s_waitcnt lgkmcnt(5)
	v_mfma_f32_16x16x32_bf16 v[0:3], v[14:17], v[60:63], v[0:3]
	ds_read_b128 v[14:17], v19 offset:17536
	v_exp_f32_e32 v102, v48
	v_exp_f32_e32 v103, v49
	v_mfma_f32_16x16x32_bf16 v[6:9], v[6:9], v[56:59], 0
	v_exp_f32_e32 v104, v50
	v_exp_f32_e32 v96, v42
	v_exp_f32_e32 v97, v10
	s_waitcnt lgkmcnt(5)
	v_mfma_f32_16x16x32_bf16 v[22:25], v[22:25], v[56:59], 0
	v_exp_f32_e32 v98, v43
	v_exp_f32_e32 v99, v44
	v_exp_f32_e32 v101, v45
	s_waitcnt lgkmcnt(3)
	v_mfma_f32_16x16x32_bf16 v[30:33], v[30:33], v[56:59], 0
	v_mul_f32_e64 v75, |v64|, v83
	v_cndmask_b32_e32 v46, 0, v79, vcc
	v_cndmask_b32_e64 v47, 0, v79, s[0:1]
	v_mfma_f32_16x16x32_bf16 v[6:9], v[26:29], v[60:63], v[6:9]
	ds_read_b128 v[52:55], v18 offset:128
	ds_read_b128 v[26:29], v19 offset:21888
	v_exp_f32_e32 v100, v11
	v_ldexp_f32 v10, v96, v46
	s_waitcnt lgkmcnt(4)
	v_mfma_f32_16x16x32_bf16 v[22:25], v[34:37], v[60:63], v[22:25]
	v_ldexp_f32 v11, v97, v47
	v_cmp_gt_f32_e32 vcc, s53, v75
	v_cndmask_b32_e64 v77, 0, v79, s[4:5]
	s_waitcnt lgkmcnt(3)
	v_mfma_f32_16x16x32_bf16 v[30:33], v[38:41], v[60:63], v[30:33]
	ds_read_b128 v[48:51], v18 offset:192
	ds_read_b128 v[34:37], v19 offset:17600
	ds_read_b128 v[38:41], v19 offset:26240
	v_cndmask_b32_e64 v84, 0, v79, s[6:7]
	v_ldexp_f32 v18, v98, v77
	s_waitcnt lgkmcnt(4)
	v_mfma_f32_16x16x32_bf16 v[0:3], v[14:17], v[52:55], v[0:3]
	ds_read_b128 v[14:17], v19 offset:21952
	ds_read_b128 v[42:45], v19 offset:30592
	v_exp_f32_e32 v13, v13
	v_exp_f32_e32 v91, v91
	s_waitcnt lgkmcnt(3)
	v_mfma_f32_16x16x32_bf16 v[0:3], v[34:37], v[48:51], v[0:3]
	v_exp_f32_e32 v93, v93
	v_cndmask_b32_e64 v90, 0, v79, s[18:19]
	v_cndmask_b32_e64 v89, 0, v79, s[16:17]
	v_mfma_f32_16x16x32_bf16 v[6:9], v[26:29], v[52:55], v[6:9]
	ds_read_b128 v[26:29], v19 offset:26304
	s_nop 2
	v_pk_mul_f32 v[10:11], v[10:11], v[0:1]
	v_cndmask_b32_e32 v0, 0, v78, vcc
	v_fma_f32 v0, |v64|, v83, v0
	v_subrev_u32_e32 v1, 50, v69
	s_waitcnt lgkmcnt(3)
	v_mfma_f32_16x16x32_bf16 v[22:25], v[38:41], v[52:55], v[22:25]
	v_exp_f32_e32 v0, v0
	v_cvt_f32_i32_e32 v1, v1
	ds_read_b128 v[38:41], v19 offset:30656
	v_ldexp_f32 v19, v99, v84
	v_pk_mul_f32 v[18:19], v[18:19], v[2:3]
	v_cndmask_b32_e32 v2, 0, v79, vcc
	s_waitcnt lgkmcnt(3)
	v_mfma_f32_16x16x32_bf16 v[6:9], v[14:17], v[48:51], v[6:9]
	v_lshlrev_b32_e32 v64, 3, v21
	v_cndmask_b32_e64 v92, 0, v79, s[20:21]
	v_cndmask_b32_e64 v94, 0, v79, s[22:23]
	s_waitcnt lgkmcnt(1)
	v_mfma_f32_16x16x32_bf16 v[14:17], v[26:29], v[48:51], v[22:25]
	v_ldexp_f32 v29, v0, v2
	v_mul_f32_e64 v0, |v1|, v83
	v_cmp_gt_f32_e32 vcc, s53, v0
	v_mfma_f32_16x16x32_bf16 v[30:33], v[42:45], v[52:55], v[30:33]
	v_ldexp_f32 v43, v13, v90
	v_cndmask_b32_e32 v0, 0, v78, vcc
	v_fma_f32 v13, |v1|, v83, v0
	v_mul_u32_u24_e32 v0, 0x90, v20
	v_add3_u32 v21, v4, v64, v0
	v_exp_f32_e32 v5, v5
	v_ldexp_f32 v42, v104, v89
	v_ldexp_f32 v26, v91, v92
	v_ldexp_f32 v27, v93, v94
	v_add_u32_e32 v92, 0x9800, v21
	v_pk_mul_f32 v[46:47], v[42:43], v[14:15]
	v_pk_mul_f32 v[90:91], v[26:27], v[16:17]
	ds_read2_b64 v[14:17], v92 offset0:64 offset1:68
	v_exp_f32_e32 v13, v13
	v_cndmask_b32_e64 v95, 0, v79, s[24:25]
	v_ldexp_f32 v28, v5, v95
	v_cvt_pk_bf16_f32 v5, v18, v19
	v_cndmask_b32_e32 v18, 0, v79, vcc
	v_ldexp_f32 v18, v13, v18
	v_subrev_u32_e32 v13, 51, v69
	v_cndmask_b32_e64 v85, 0, v79, s[8:9]
	v_cndmask_b32_e64 v86, 0, v79, s[10:11]
	v_cndmask_b32_e64 v87, 0, v79, s[12:13]
	v_cndmask_b32_e64 v88, 0, v79, s[14:15]
	s_waitcnt lgkmcnt(1)
	v_mfma_f32_16x16x32_bf16 v[22:25], v[38:41], v[48:51], v[30:33]
	v_cvt_f32_i32_e32 v13, v13
	v_ldexp_f32 v34, v100, v85
	v_ldexp_f32 v35, v101, v86
	v_ldexp_f32 v36, v102, v87
	v_ldexp_f32 v37, v103, v88
	v_pk_mul_f32 v[6:7], v[34:35], v[6:7]
	v_pk_mul_f32 v[30:31], v[36:37], v[8:9]
	v_add_u32_e32 v75, 0x8800, v21
	v_cvt_pk_bf16_f32 v4, v10, v11
	v_add_u32_e32 v77, 0x9000, v21
	v_cvt_pk_bf16_f32 v6, v6, v7
	v_cvt_pk_bf16_f32 v7, v30, v31
	v_add_u32_e32 v93, 0xa000, v21
	v_add_u32_e32 v94, 0xa800, v21
	v_add_u32_e32 v69, 0xb000, v21
	v_add_u32_e32 v95, 0xb800, v21
	v_add_u32_e32 v96, 0xc000, v21
	v_pk_mul_f32 v[22:23], v[28:29], v[22:23]
	ds_read2_b64 v[0:3], v75 offset1:4
	ds_read2_b64 v[8:11], v77 offset0:32 offset1:36
	ds_read2_b64 v[26:29], v93 offset0:96 offset1:100
	ds_read2_b64 v[30:33], v94 offset0:128 offset1:132
	s_waitcnt lgkmcnt(4)
	v_mfma_f32_16x16x32_bf16 v[34:37], v[14:17], v[4:7], 0
	ds_read2_b64 v[14:17], v69 offset0:160 offset1:164
	v_mul_f32_e64 v19, |v13|, v83
	ds_read2_b64 v[38:41], v95 offset0:192 offset1:196
	ds_read2_b64 v[42:45], v96 offset0:224 offset1:228
	v_cmp_gt_f32_e32 vcc, s53, v19
	s_waitcnt lgkmcnt(6)
	v_mfma_f32_16x16x32_bf16 v[0:3], v[0:3], v[4:7], 0
	v_cvt_pk_bf16_f32 v89, v90, v91
	v_cndmask_b32_e32 v19, 0, v78, vcc
	v_fma_f32 v13, |v13|, v83, v19
	v_exp_f32_e32 v13, v13
	v_cndmask_b32_e32 v19, 0, v79, vcc
	s_waitcnt lgkmcnt(5)
	v_mfma_f32_16x16x32_bf16 v[8:11], v[8:11], v[4:7], 0
	v_cvt_pk_bf16_f32 v90, v22, v23
	v_ldexp_f32 v19, v13, v19
	v_pk_mul_f32 v[18:19], v[18:19], v[24:25]
	s_waitcnt lgkmcnt(4)
	v_mfma_f32_16x16x32_bf16 v[26:29], v[26:29], v[4:7], 0
	ds_read2_b64 v[22:25], v92 offset0:72 offset1:76
	v_cvt_pk_bf16_f32 v88, v46, v47
	v_cvt_pk_bf16_f32 v91, v18, v19
	s_waitcnt lgkmcnt(4)
	v_mfma_f32_16x16x32_bf16 v[30:33], v[30:33], v[4:7], 0
	v_ashrrev_i32_e32 v13, 31, v12
	v_lshlrev_b64 v[12:13], 15, v[12:13]
	v_lshlrev_b32_e32 v20, 8, v20
	s_waitcnt lgkmcnt(3)
	v_mfma_f32_16x16x32_bf16 v[84:87], v[14:17], v[4:7], 0
	ds_read2_b64 v[14:17], v75 offset0:8 offset1:12
	v_mov_b32_e32 v75, v65
	v_mov_b32_e32 v21, v65
	s_waitcnt lgkmcnt(3)
	v_mfma_f32_16x16x32_bf16 v[38:41], v[38:41], v[4:7], 0
	v_readlane_b32 s4, v255, 2
	v_readlane_b32 s6, v255, 4
	v_readlane_b32 s7, v255, 5
	s_waitcnt lgkmcnt(2)
	v_mfma_f32_16x16x32_bf16 v[42:45], v[42:45], v[4:7], 0
	ds_read2_b64 v[4:7], v77 offset0:40 offset1:44
	v_mov_b32_e32 v77, v65
	v_readlane_b32 s5, v255, 3
	s_waitcnt lgkmcnt(1)
	v_mfma_f32_16x16x32_bf16 v[16:19], v[14:17], v[88:91], v[0:3]
	v_readlane_b32 s8, v255, 6
	v_readlane_b32 s9, v255, 7
	v_readlane_b32 s10, v255, 8
	s_waitcnt lgkmcnt(0)
	v_mfma_f32_16x16x32_bf16 v[0:3], v[4:7], v[88:91], v[8:11]
	v_readlane_b32 s11, v255, 9
	s_nop 1
	ds_read2_b64 v[8:11], v93 offset0:104 offset1:108
	v_readlane_b32 s12, v255, 10
	v_mfma_f32_16x16x32_bf16 v[4:7], v[22:25], v[88:91], v[34:37]
	ds_read2_b64 v[22:25], v94 offset0:136 offset1:140
	v_readlane_b32 s13, v255, 11
	v_readlane_b32 s14, v255, 12
	s_waitcnt lgkmcnt(1)
	v_mfma_f32_16x16x32_bf16 v[8:11], v[8:11], v[88:91], v[26:29]
	s_nop 2
	v_lshl_add_u64 v[26:27], s[42:43], 0, v[12:13]
	v_lshl_add_u64 v[26:27], v[26:27], 0, v[74:75]
	v_lshl_add_u64 v[108:109], v[26:27], 0, v[20:21]
	s_waitcnt lgkmcnt(0)
	v_mfma_f32_16x16x32_bf16 v[12:15], v[22:25], v[88:91], v[30:33]
	ds_read2_b64 v[22:25], v69 offset0:168 offset1:172
	v_add_co_u32_e32 v134, vcc, s63, v108
	s_nop 1
	v_addc_co_u32_e32 v135, vcc, 0, v109, vcc
	v_add_co_u32_e32 v136, vcc, s64, v108
	s_nop 1
	v_addc_co_u32_e32 v137, vcc, 0, v109, vcc
	v_add_co_u32_e32 v138, vcc, s65, v108
	s_nop 1
	v_addc_co_u32_e32 v139, vcc, 0, v109, vcc
	v_add_co_u32_e32 v140, vcc, s66, v108
	s_nop 1
	v_addc_co_u32_e32 v141, vcc, 0, v109, vcc
	v_add_co_u32_e32 v142, vcc, s67, v108
	s_nop 1
	v_addc_co_u32_e32 v143, vcc, 0, v109, vcc
	v_add_co_u32_e32 v150, vcc, s68, v108
	s_nop 1
	v_addc_co_u32_e32 v151, vcc, 0, v109, vcc
	v_add_co_u32_e32 v152, vcc, s69, v108
	s_nop 1
	v_addc_co_u32_e32 v153, vcc, 0, v109, vcc
	global_load_dwordx4 v[160:163], v[108:109], off
	global_load_dwordx4 v[164:167], v[108:109], off offset:64
	global_load_dwordx4 v[168:171], v[108:109], off offset:128
	global_load_dwordx4 v[172:175], v[108:109], off offset:192
	global_load_dwordx4 v[176:179], v[134:135], off
	global_load_dwordx4 v[180:183], v[134:135], off offset:64
	global_load_dwordx4 v[184:187], v[134:135], off offset:128
	global_load_dwordx4 v[188:191], v[134:135], off offset:192
	global_load_dwordx4 v[192:195], v[136:137], off
	global_load_dwordx4 v[196:199], v[136:137], off offset:64
	global_load_dwordx4 v[200:203], v[136:137], off offset:128
	global_load_dwordx4 v[204:207], v[136:137], off offset:192
	global_load_dwordx4 v[208:211], v[138:139], off
	global_load_dwordx4 v[212:215], v[138:139], off offset:64
	global_load_dwordx4 v[216:219], v[138:139], off offset:128
	global_load_dwordx4 v[220:223], v[138:139], off offset:192
	global_load_dwordx4 v[224:227], v[140:141], off
	global_load_dwordx4 v[228:231], v[140:141], off offset:64
	global_load_dwordx4 v[232:235], v[140:141], off offset:128
	global_load_dwordx4 v[236:239], v[140:141], off offset:192
	global_load_dwordx4 v[240:243], v[142:143], off
	global_load_dwordx4 v[244:247], v[142:143], off offset:64
	global_load_dwordx4 v[248:251], v[142:143], off offset:128
	ds_read2_b64 v[30:33], v95 offset0:200 offset1:204
	s_waitcnt lgkmcnt(0)
	v_mfma_f32_16x16x32_bf16 v[20:23], v[22:25], v[88:91], v[84:87]
	v_ashrrev_i32_e32 v69, 31, v68
	v_mfma_f32_16x16x32_bf16 v[84:87], v[30:33], v[88:91], v[38:41]
	ds_read2_b64 v[30:33], v96 offset0:232 offset1:236
	s_waitcnt lgkmcnt(0)
	v_mfma_f32_16x16x32_bf16 v[88:91], v[30:33], v[88:91], v[42:45]
	s_nop 0
	s_waitcnt lgkmcnt(0)
	global_load_dwordx4 v[96:99], v[142:143], off offset:192
	global_load_dwordx4 v[100:103], v[150:151], off
	global_load_dwordx4 v[104:107], v[150:151], off offset:64
	s_waitcnt vmcnt(22)
	v_mfma_f32_16x16x32_bf16 v[36:39], v[160:163], v[56:59], 0
	v_mfma_f32_16x16x32_bf16 v[36:39], v[164:167], v[60:63], v[36:39]
	v_mfma_f32_16x16x32_bf16 v[36:39], v[168:171], v[52:55], v[36:39]
	v_mfma_f32_16x16x32_bf16 v[36:39], v[172:175], v[48:51], v[36:39]
	global_load_dwordx4 v[160:163], v[150:151], off offset:128
	global_load_dwordx4 v[164:167], v[150:151], off offset:192
	global_load_dwordx4 v[168:171], v[152:153], off
	global_load_dwordx4 v[172:175], v[152:153], off offset:64
	s_waitcnt vmcnt(22)
	v_mfma_f32_16x16x32_bf16 v[24:27], v[176:179], v[56:59], 0
	v_mfma_f32_16x16x32_bf16 v[24:27], v[180:183], v[60:63], v[24:27]
	v_mfma_f32_16x16x32_bf16 v[24:27], v[184:187], v[52:55], v[24:27]
	v_mfma_f32_16x16x32_bf16 v[24:27], v[188:191], v[48:51], v[24:27]
	global_load_dwordx4 v[176:179], v[152:153], off offset:128
	global_load_dwordx4 v[180:183], v[152:153], off offset:192
	s_waitcnt vmcnt(20)
	v_mfma_f32_16x16x32_bf16 v[28:31], v[192:195], v[56:59], 0
	v_mfma_f32_16x16x32_bf16 v[28:31], v[196:199], v[60:63], v[28:31]
	v_mfma_f32_16x16x32_bf16 v[28:31], v[200:203], v[52:55], v[28:31]
	v_mfma_f32_16x16x32_bf16 v[28:31], v[204:207], v[48:51], v[28:31]
	s_waitcnt vmcnt(16)
	v_mfma_f32_16x16x32_bf16 v[32:35], v[208:211], v[56:59], 0
	v_mfma_f32_16x16x32_bf16 v[32:35], v[212:215], v[60:63], v[32:35]
	v_mfma_f32_16x16x32_bf16 v[32:35], v[216:219], v[52:55], v[32:35]
	v_mfma_f32_16x16x32_bf16 v[32:35], v[220:223], v[48:51], v[32:35]
	s_waitcnt vmcnt(12)
	v_mfma_f32_16x16x32_bf16 v[40:43], v[224:227], v[56:59], 0
	v_mfma_f32_16x16x32_bf16 v[40:43], v[228:231], v[60:63], v[40:43]
	v_mfma_f32_16x16x32_bf16 v[40:43], v[232:235], v[52:55], v[40:43]
	v_mfma_f32_16x16x32_bf16 v[40:43], v[236:239], v[48:51], v[40:43]
	s_waitcnt vmcnt(8)
	v_mfma_f32_16x16x32_bf16 v[44:47], v[240:243], v[56:59], 0
	v_mfma_f32_16x16x32_bf16 v[44:47], v[244:247], v[60:63], v[44:47]
	v_mfma_f32_16x16x32_bf16 v[44:47], v[248:251], v[52:55], v[44:47]
	v_mfma_f32_16x16x32_bf16 v[44:47], v[96:99], v[48:51], v[44:47]
	s_waitcnt vmcnt(4)
	v_mfma_f32_16x16x32_bf16 v[92:95], v[100:103], v[56:59], 0
	v_mfma_f32_16x16x32_bf16 v[92:95], v[104:107], v[60:63], v[92:95]
	v_mfma_f32_16x16x32_bf16 v[92:95], v[160:163], v[52:55], v[92:95]
	v_mfma_f32_16x16x32_bf16 v[92:95], v[164:167], v[48:51], v[92:95]
	s_waitcnt vmcnt(0)
	v_mfma_f32_16x16x32_bf16 v[56:59], v[168:171], v[56:59], 0
	v_mfma_f32_16x16x32_bf16 v[56:59], v[172:175], v[60:63], v[56:59]
	v_mfma_f32_16x16x32_bf16 v[52:55], v[176:179], v[52:55], v[56:59]
	v_mfma_f32_16x16x32_bf16 v[48:51], v[180:183], v[48:51], v[52:55]
	v_readlane_b32 s15, v255, 13
	v_readlane_b32 s16, v255, 14
	v_readlane_b32 s17, v255, 15
	v_readlane_b32 s18, v255, 16
	v_readlane_b32 s19, v255, 17
	s_waitcnt lgkmcnt(0)
	s_nop 5
	s_waitcnt lgkmcnt(0)
	s_nop 2
	s_nop 2
	s_waitcnt lgkmcnt(0)
	s_nop 0
	s_nop 3
	s_waitcnt lgkmcnt(0)
	s_waitcnt lgkmcnt(0)
	s_waitcnt lgkmcnt(0)
	s_nop 0
	s_waitcnt lgkmcnt(0)
	s_nop 0
	s_waitcnt lgkmcnt(0)
	s_waitcnt lgkmcnt(0)
	s_nop 0
	s_waitcnt lgkmcnt(0)
	v_lshl_add_u64 v[100:101], v[68:69], 0, v[76:77]
	v_mad_u64_u32 v[60:61], s[0:1], v100, s57, v[66:67]
	v_mad_i32_i24 v61, v101, s57, v61
	v_lshl_add_u64 v[60:61], v[60:61], 0, v[72:73]
	v_lshl_add_u64 v[102:103], v[60:61], 0, v[64:65]
	v_add_co_u32_e32 v60, vcc, s63, v102
	s_waitcnt lgkmcnt(0)
	v_addc_co_u32_e32 v61, vcc, 0, v103, vcc
	flat_load_dwordx2 v[68:69], v[60:61] offset:512
	v_lshl_add_u64 v[232:233], v[102:103], 0, s[46:47]
	v_lshl_add_u64 v[234:235], v[70:71], 2, s[6:7]
	v_lshl_add_u64 v[234:235], v[234:235], 0, v[74:75]
	global_load_dwordx2 v[186:187], v[232:233], off offset:32
	global_load_dwordx2 v[188:189], v[232:233], off offset:64
	global_load_dwordx2 v[190:191], v[232:233], off offset:96
	global_load_dwordx2 v[192:193], v[232:233], off offset:128
	global_load_dwordx2 v[194:195], v[232:233], off offset:160
	global_load_dwordx2 v[196:197], v[232:233], off offset:192
	global_load_dwordx2 v[198:199], v[232:233], off offset:224
	global_load_dwordx4 v[204:207], v[234:235], off offset:64
	global_load_dwordx4 v[208:211], v[234:235], off offset:128
	global_load_dwordx4 v[212:215], v[234:235], off offset:192
	global_load_dwordx4 v[216:219], v[234:235], off offset:256
	global_load_dwordx4 v[220:223], v[234:235], off offset:320
	global_load_dwordx4 v[224:227], v[234:235], off offset:384
	global_load_dwordx4 v[228:231], v[234:235], off offset:448
	s_nop 0
	v_add_u32_e32 v56, 1, v76
	v_cvt_f32_ubyte0_e32 v56, v56
	v_mul_f32_e32 v57, v83, v56
	v_cmp_gt_f32_e32 vcc, s53, v57
	s_waitcnt vmcnt(0) lgkmcnt(0)
	v_lshlrev_b32_e32 v77, 16, v68
	v_cndmask_b32_e32 v57, 0, v78, vcc
	v_fmac_f32_e32 v57, v83, v56
	v_exp_f32_e32 v56, v57
	v_cndmask_b32_e32 v52, 0, v79, vcc
	v_and_b32_e32 v68, 0xffff0000, v68
	v_cmp_lt_i32_e32 vcc, v157, v156
	v_ldexp_f32 v62, v56, v52
	v_pk_fma_f32 v[58:59], v[62:63], v[50:51], v[90:91] op_sel_hi:[0,1,1]
	v_lshlrev_b64 v[50:51], 11, v[100:101]
	v_lshl_add_u64 v[50:51], s[30:31], 0, v[50:51]
	v_lshl_add_u64 v[52:53], v[50:51], 0, v[72:73]
	v_mul_f32_e32 v72, 0xbfb8aa3b, v77
	v_pk_fma_f32 v[54:55], v[62:63], v[92:93], v[84:85] op_sel_hi:[0,1,1]
	v_exp_f32_e32 v84, v72
	v_mul_f32_e32 v72, 0xbfb8aa3b, v68
	v_exp_f32_e32 v85, v72
	v_pk_fma_f32 v[60:61], v[62:63], v[48:49], v[88:89] op_sel_hi:[0,1,1]
	v_cndmask_b32_e32 v48, v155, v157, vcc
	v_cmp_lt_i32_e32 vcc, v158, v156
	v_lshlrev_b32_e32 v76, 2, v48
	v_pk_fma_f32 v[56:57], v[62:63], v[94:95], v[86:87] op_sel_hi:[0,1,1]
	v_cndmask_b32_e32 v48, v155, v158, vcc
	v_lshlrev_b32_e32 v63, 2, v48
	v_pk_fma_f32 v[18:19], v[62:63], v[38:39], v[18:19] op_sel_hi:[0,1,1]
	v_pk_add_f32 v[38:39], v[84:85], 1.0 op_sel_hi:[1,0]
	v_lshlrev_b32_e32 v83, 16, v69
	v_and_b32_e32 v86, 0xffff0000, v69
	v_div_scale_f32 v69, s[0:1], v39, v39, v68
	v_rcp_f32_e32 v84, v69
	v_pk_fma_f32 v[16:17], v[62:63], v[36:37], v[16:17] op_sel_hi:[0,1,1]
	v_add_f32_e32 v36, 0, v16
	v_add_f32_e32 v85, v17, v36
	v_fma_f32 v36, -v69, v84, 1.0
	v_fmac_f32_e32 v84, v36, v84
	v_div_scale_f32 v36, vcc, v68, v39, v68
	v_mul_f32_e32 v37, v36, v84
	v_fma_f32 v87, -v69, v37, v36
	v_fmac_f32_e32 v37, v87, v84
	v_div_scale_f32 v87, s[0:1], v38, v38, v77
	v_rcp_f32_e32 v88, v87
	v_fma_f32 v36, -v69, v37, v36
	v_div_fmas_f32 v36, v36, v84, v37
	v_div_fixup_f32 v37, v36, v39, v68
	v_fma_f32 v36, -v87, v88, 1.0
	v_fmac_f32_e32 v88, v36, v88
	v_div_scale_f32 v36, vcc, v77, v38, v77
	v_mul_f32_e32 v39, v36, v88
	v_fma_f32 v68, -v87, v39, v36
	v_fmac_f32_e32 v39, v68, v88
	v_fma_f32 v36, -v87, v39, v36
	v_div_fmas_f32 v36, v36, v88, v39
	v_div_fixup_f32 v36, v36, v38, v77
	v_add_f32_e32 v38, v18, v85
	v_add_f32_e32 v38, v19, v38
	v_pk_fma_f32 v[0:1], v[62:63], v[24:25], v[0:1] op_sel_hi:[0,1,1]
	v_add_f32_e32 v24, v38, v0
	v_pk_fma_f32 v[2:3], v[62:63], v[26:27], v[2:3] op_sel_hi:[0,1,1]
	v_add_f32_e32 v24, v1, v24
	v_add_f32_e32 v24, v2, v24
	v_add_f32_e32 v24, v3, v24
	v_pk_fma_f32 v[4:5], v[62:63], v[28:29], v[4:5] op_sel_hi:[0,1,1]
	v_add_f32_e32 v24, v24, v4
	v_pk_fma_f32 v[6:7], v[62:63], v[30:31], v[6:7] op_sel_hi:[0,1,1]
	v_add_f32_e32 v24, v5, v24
	v_add_f32_e32 v24, v6, v24
	v_add_f32_e32 v24, v7, v24
	v_pk_fma_f32 v[8:9], v[62:63], v[32:33], v[8:9] op_sel_hi:[0,1,1]
	v_add_f32_e32 v24, v24, v8
	v_pk_fma_f32 v[10:11], v[62:63], v[34:35], v[10:11] op_sel_hi:[0,1,1]
	v_add_f32_e32 v24, v9, v24
	v_add_f32_e32 v24, v10, v24
	v_add_f32_e32 v24, v11, v24
	v_pk_fma_f32 v[12:13], v[62:63], v[40:41], v[12:13] op_sel_hi:[0,1,1]
	v_add_f32_e32 v24, v24, v12
	v_pk_fma_f32 v[14:15], v[62:63], v[42:43], v[14:15] op_sel_hi:[0,1,1]
	v_add_f32_e32 v24, v13, v24
	v_lshl_add_u64 v[48:49], v[70:71], 2, s[6:7]
	v_add_f32_e32 v24, v14, v24
	v_lshl_add_u64 v[48:49], v[48:49], 0, v[74:75]
	v_add_f32_e32 v28, v15, v24
	v_pk_fma_f32 v[26:27], v[62:63], v[44:45], v[20:21] op_sel_hi:[0,1,1]
	global_load_dwordx4 v[72:75], v[48:49], off
	v_add_f32_e32 v20, v28, v26
	v_pk_fma_f32 v[24:25], v[62:63], v[46:47], v[22:23] op_sel_hi:[0,1,1]
	v_add_f32_e32 v20, v27, v20
	v_add_f32_e32 v20, v24, v20
	v_add_f32_e32 v20, v25, v20
	v_add_f32_e32 v20, v20, v54
	v_add_f32_e32 v20, v55, v20
	v_mul_f32_e32 v68, 0xbfb8aa3b, v83
	v_mul_f32_e32 v69, 0xbfb8aa3b, v86
	v_add_f32_e32 v20, v56, v20
	v_exp_f32_e32 v68, v68
	v_exp_f32_e32 v69, v69
	v_add_f32_e32 v20, v57, v20
	v_add_f32_e32 v20, v20, v60
	v_add_f32_e32 v20, v61, v20
	v_add_f32_e32 v20, v58, v20
	v_pk_add_f32 v[68:69], v[68:69], 1.0 op_sel_hi:[1,0]
	v_add_f32_e32 v20, v59, v20
	v_div_scale_f32 v39, s[0:1], v69, v69, v86
	ds_bpermute_b32 v21, v76, v20
	v_rcp_f32_e32 v84, v39
	v_lshl_add_u64 v[50:51], v[102:103], 0, s[46:47]
	v_fma_f32 v77, -v39, v84, 1.0
	s_waitcnt lgkmcnt(0)
	v_add_f32_e32 v20, v20, v21
	v_fmac_f32_e32 v84, v77, v84
	v_div_scale_f32 v77, vcc, v86, v69, v86
	ds_bpermute_b32 v21, v63, v20
	v_mul_f32_e32 v85, v77, v84
	v_fma_f32 v87, -v39, v85, v77
	v_fmac_f32_e32 v85, v87, v84
	v_fma_f32 v22, -v39, v85, v77
	v_div_fmas_f32 v22, v22, v84, v85
	s_waitcnt lgkmcnt(0)
	v_add_f32_e32 v20, v20, v21
	v_div_fixup_f32 v29, v22, v69, v86
	v_mul_f32_e32 v28, 0x3c000000, v20
	v_pk_add_f32 v[32:33], v[16:17], v[28:29] op_sel_hi:[1,0] neg_lo:[0,1] neg_hi:[0,1]
	v_pk_add_f32 v[38:39], v[18:19], v[28:29] op_sel_hi:[1,0] neg_lo:[0,1] neg_hi:[0,1]
	v_pk_mul_f32 v[34:35], v[32:33], v[32:33]
	v_pk_mul_f32 v[40:41], v[38:39], v[38:39]
	v_pk_add_f32 v[42:43], v[0:1], v[28:29] op_sel_hi:[1,0] neg_lo:[0,1] neg_hi:[0,1]
	v_pk_add_f32 v[46:47], v[2:3], v[28:29] op_sel_hi:[1,0] neg_lo:[0,1] neg_hi:[0,1]
	v_pk_add_f32 v[84:85], v[4:5], v[28:29] op_sel_hi:[1,0] neg_lo:[0,1] neg_hi:[0,1]
	v_pk_add_f32 v[88:89], v[6:7], v[28:29] op_sel_hi:[1,0] neg_lo:[0,1] neg_hi:[0,1]
	v_pk_add_f32 v[22:23], v[8:9], v[28:29] op_sel_hi:[1,0] neg_lo:[0,1] neg_hi:[0,1]
	v_pk_add_f32 v[20:21], v[10:11], v[28:29] op_sel_hi:[1,0] neg_lo:[0,1] neg_hi:[0,1]
	v_pk_add_f32 v[18:19], v[12:13], v[28:29] op_sel_hi:[1,0] neg_lo:[0,1] neg_hi:[0,1]
	v_pk_add_f32 v[16:17], v[14:15], v[28:29] op_sel_hi:[1,0] neg_lo:[0,1] neg_hi:[0,1]
	v_pk_add_f32 v[14:15], v[26:27], v[28:29] op_sel_hi:[1,0] neg_lo:[0,1] neg_hi:[0,1]
	v_pk_add_f32 v[12:13], v[24:25], v[28:29] op_sel_hi:[1,0] neg_lo:[0,1] neg_hi:[0,1]
	v_pk_add_f32 v[4:5], v[60:61], v[28:29] op_sel_hi:[1,0] neg_lo:[0,1] neg_hi:[0,1]
	v_pk_add_f32 v[0:1], v[58:59], v[28:29] op_sel_hi:[1,0] neg_lo:[0,1] neg_hi:[0,1]
	v_pk_add_f32 v[8:9], v[56:57], v[28:29] op_sel_hi:[1,0] neg_lo:[0,1] neg_hi:[0,1]
	v_pk_add_f32 v[10:11], v[54:55], v[28:29] op_sel_hi:[1,0] neg_lo:[0,1] neg_hi:[0,1]
	v_add_f32_e32 v28, v34, v35
	v_add_f32_e32 v28, v40, v28
	v_pk_mul_f32 v[44:45], v[42:43], v[42:43]
	v_add_f32_e32 v28, v41, v28
	v_add_f32_e32 v28, v44, v28
	v_pk_mul_f32 v[2:3], v[46:47], v[46:47]
	v_add_f32_e32 v28, v45, v28
	v_add_f32_e32 v2, v2, v28
	v_pk_mul_f32 v[86:87], v[84:85], v[84:85]
	v_add_f32_e32 v2, v3, v2
	v_add_f32_e32 v2, v86, v2
	v_pk_mul_f32 v[6:7], v[88:89], v[88:89]
	v_add_f32_e32 v2, v87, v2
	v_add_f32_e32 v2, v6, v2
	v_pk_mul_f32 v[90:91], v[22:23], v[22:23]
	v_add_f32_e32 v2, v7, v2
	v_add_f32_e32 v2, v90, v2
	v_pk_mul_f32 v[92:93], v[20:21], v[20:21]
	v_add_f32_e32 v2, v91, v2
	v_add_f32_e32 v2, v92, v2
	v_pk_mul_f32 v[94:95], v[18:19], v[18:19]
	v_add_f32_e32 v2, v93, v2
	v_add_f32_e32 v2, v94, v2
	v_pk_mul_f32 v[96:97], v[16:17], v[16:17]
	v_add_f32_e32 v2, v95, v2
	v_add_f32_e32 v2, v96, v2
	v_pk_mul_f32 v[26:27], v[14:15], v[14:15]
	v_add_f32_e32 v2, v97, v2
	v_add_f32_e32 v2, v26, v2
	v_pk_mul_f32 v[24:25], v[12:13], v[12:13]
	v_add_f32_e32 v2, v27, v2
	v_add_f32_e32 v2, v24, v2
	v_pk_mul_f32 v[54:55], v[10:11], v[10:11]
	v_add_f32_e32 v2, v25, v2
	v_add_f32_e32 v2, v54, v2
	v_pk_mul_f32 v[56:57], v[8:9], v[8:9]
	v_add_f32_e32 v2, v55, v2
	v_add_f32_e32 v2, v56, v2
	v_pk_mul_f32 v[60:61], v[4:5], v[4:5]
	v_add_f32_e32 v2, v57, v2
	v_add_f32_e32 v2, v60, v2
	v_pk_mul_f32 v[58:59], v[0:1], v[0:1]
	v_add_f32_e32 v2, v61, v2
	v_add_f32_e32 v2, v58, v2
	v_add_f32_e32 v2, v59, v2
	ds_bpermute_b32 v3, v76, v2
	v_div_scale_f32 v62, s[0:1], v68, v68, v83
	v_rcp_f32_e32 v69, v62
	s_waitcnt vmcnt(0)
	v_lshlrev_b32_e32 v40, 16, v31
	s_waitcnt lgkmcnt(0)
	v_add_f32_e32 v2, v2, v3
	ds_bpermute_b32 v3, v63, v2
	v_fma_f32 v6, -v62, v69, 1.0
	v_fmac_f32_e32 v69, v6, v69
	v_div_scale_f32 v6, vcc, v83, v68, v83
	s_waitcnt lgkmcnt(0)
	v_add_f32_e32 v2, v2, v3
	v_fmamk_f32 v2, v2, 0x3c000000, v81
	v_mul_f32_e32 v7, v6, v69
	v_mul_f32_e32 v3, 0x4b800000, v2
	v_cmp_gt_f32_e64 s[0:1], s54, v2
	v_fma_f32 v24, -v62, v7, v6
	v_fmac_f32_e32 v7, v24, v69
	v_cndmask_b32_e64 v2, v2, v3, s[0:1]
	v_rsq_f32_e32 v24, v2
	v_fma_f32 v6, -v62, v7, v6
	v_div_fmas_f32 v2, v6, v69, v7
	v_div_fixup_f32 v28, v2, v68, v83
	v_mul_f32_e32 v6, 0x45800000, v24
	v_cndmask_b32_e64 v6, v24, v6, s[0:1]
	v_pk_mul_f32 v[24:25], v[32:33], v[6:7] op_sel_hi:[1,0]
	v_pk_mul_f32 v[26:27], v[38:39], v[6:7] op_sel_hi:[1,0]
	v_pk_mul_f32 v[24:25], v[72:73], v[24:25]
	v_pk_mul_f32 v[26:27], v[74:75], v[26:27]
	v_pk_mul_f32 v[24:25], v[36:37], v[24:25]
	v_pk_mul_f32 v[26:27], v[28:29], v[26:27]
	v_lshl_add_u64 v[2:3], v[52:53], 0, v[64:65]
	v_cvt_pk_bf16_f32 v24, v24, v25
	v_cvt_pk_bf16_f32 v25, v26, v27
	flat_store_dwordx2 v[2:3], v[24:25]
	v_lshlrev_b32_e32 v32, 16, v186
	v_and_b32_e32 v33, 0xffff0000, v186
	v_lshlrev_b32_e32 v34, 16, v187
	v_and_b32_e32 v35, 0xffff0000, v187
	v_mul_f32_e32 v36, 0xbfb8aa3b, v32
	v_mul_f32_e32 v37, 0xbfb8aa3b, v33
	v_mul_f32_e32 v38, 0xbfb8aa3b, v34
	v_mul_f32_e32 v39, 0xbfb8aa3b, v35
	v_exp_f32_e32 v36, v36
	v_exp_f32_e32 v37, v37
	v_exp_f32_e32 v38, v38
	v_exp_f32_e32 v39, v39
	v_pk_mul_f32 v[42:43], v[42:43], v[6:7] op_sel_hi:[1,0]
	v_pk_mul_f32 v[46:47], v[46:47], v[6:7] op_sel_hi:[1,0]
	v_pk_add_f32 v[36:37], v[36:37], 1.0 op_sel_hi:[1,0]
	v_pk_add_f32 v[38:39], v[38:39], 1.0 op_sel_hi:[1,0]
	v_pk_mul_f32 v[42:43], v[204:205], v[42:43]
	v_pk_mul_f32 v[46:47], v[206:207], v[46:47]
	v_rcp_f32_e32 v36, v36
	v_rcp_f32_e32 v37, v37
	v_rcp_f32_e32 v38, v38
	v_rcp_f32_e32 v39, v39
	v_pk_mul_f32 v[32:33], v[32:33], v[36:37]
	v_pk_mul_f32 v[34:35], v[34:35], v[38:39]
	v_pk_mul_f32 v[42:43], v[32:33], v[42:43]
	v_pk_mul_f32 v[46:47], v[34:35], v[46:47]
	v_cvt_pk_bf16_f32 v44, v42, v43
	v_cvt_pk_bf16_f32 v45, v46, v47
	global_store_dwordx2 v[2:3], v[44:45], off offset:32
	v_lshlrev_b32_e32 v24, 16, v188
	v_and_b32_e32 v25, 0xffff0000, v188
	v_lshlrev_b32_e32 v26, 16, v189
	v_and_b32_e32 v27, 0xffff0000, v189
	v_mul_f32_e32 v28, 0xbfb8aa3b, v24
	v_mul_f32_e32 v29, 0xbfb8aa3b, v25
	v_mul_f32_e32 v30, 0xbfb8aa3b, v26
	v_mul_f32_e32 v31, 0xbfb8aa3b, v27
	v_exp_f32_e32 v28, v28
	v_exp_f32_e32 v29, v29
	v_exp_f32_e32 v30, v30
	v_exp_f32_e32 v31, v31
	v_pk_mul_f32 v[84:85], v[84:85], v[6:7] op_sel_hi:[1,0]
	v_pk_mul_f32 v[88:89], v[88:89], v[6:7] op_sel_hi:[1,0]
	v_pk_add_f32 v[28:29], v[28:29], 1.0 op_sel_hi:[1,0]
	v_pk_add_f32 v[30:31], v[30:31], 1.0 op_sel_hi:[1,0]
	v_pk_mul_f32 v[84:85], v[208:209], v[84:85]
	v_pk_mul_f32 v[88:89], v[210:211], v[88:89]
	v_rcp_f32_e32 v28, v28
	v_rcp_f32_e32 v29, v29
	v_rcp_f32_e32 v30, v30
	v_rcp_f32_e32 v31, v31
	v_pk_mul_f32 v[24:25], v[24:25], v[28:29]
	v_pk_mul_f32 v[26:27], v[26:27], v[30:31]
	v_pk_mul_f32 v[84:85], v[24:25], v[84:85]
	v_pk_mul_f32 v[88:89], v[26:27], v[88:89]
	v_cvt_pk_bf16_f32 v40, v84, v85
	v_cvt_pk_bf16_f32 v41, v88, v89
	global_store_dwordx2 v[2:3], v[40:41], off offset:64
	v_lshlrev_b32_e32 v32, 16, v190
	v_and_b32_e32 v33, 0xffff0000, v190
	v_lshlrev_b32_e32 v34, 16, v191
	v_and_b32_e32 v35, 0xffff0000, v191
	v_mul_f32_e32 v36, 0xbfb8aa3b, v32
	v_mul_f32_e32 v37, 0xbfb8aa3b, v33
	v_mul_f32_e32 v38, 0xbfb8aa3b, v34
	v_mul_f32_e32 v39, 0xbfb8aa3b, v35
	v_exp_f32_e32 v36, v36
	v_exp_f32_e32 v37, v37
	v_exp_f32_e32 v38, v38
	v_exp_f32_e32 v39, v39
	v_pk_mul_f32 v[22:23], v[22:23], v[6:7] op_sel_hi:[1,0]
	v_pk_mul_f32 v[20:21], v[20:21], v[6:7] op_sel_hi:[1,0]
	v_pk_add_f32 v[36:37], v[36:37], 1.0 op_sel_hi:[1,0]
	v_pk_add_f32 v[38:39], v[38:39], 1.0 op_sel_hi:[1,0]
	v_pk_mul_f32 v[22:23], v[212:213], v[22:23]
	v_pk_mul_f32 v[20:21], v[214:215], v[20:21]
	v_rcp_f32_e32 v36, v36
	v_rcp_f32_e32 v37, v37
	v_rcp_f32_e32 v38, v38
	v_rcp_f32_e32 v39, v39
	v_pk_mul_f32 v[32:33], v[32:33], v[36:37]
	v_pk_mul_f32 v[34:35], v[34:35], v[38:39]
	v_pk_mul_f32 v[22:23], v[32:33], v[22:23]
	v_pk_mul_f32 v[20:21], v[34:35], v[20:21]
	v_cvt_pk_bf16_f32 v44, v22, v23
	v_cvt_pk_bf16_f32 v45, v20, v21
	global_store_dwordx2 v[2:3], v[44:45], off offset:96
	v_lshlrev_b32_e32 v24, 16, v192
	v_and_b32_e32 v25, 0xffff0000, v192
	v_lshlrev_b32_e32 v26, 16, v193
	v_and_b32_e32 v27, 0xffff0000, v193
	v_mul_f32_e32 v28, 0xbfb8aa3b, v24
	v_mul_f32_e32 v29, 0xbfb8aa3b, v25
	v_mul_f32_e32 v30, 0xbfb8aa3b, v26
	v_mul_f32_e32 v31, 0xbfb8aa3b, v27
	v_exp_f32_e32 v28, v28
	v_exp_f32_e32 v29, v29
	v_exp_f32_e32 v30, v30
	v_exp_f32_e32 v31, v31
	v_pk_mul_f32 v[18:19], v[18:19], v[6:7] op_sel_hi:[1,0]
	v_pk_mul_f32 v[16:17], v[16:17], v[6:7] op_sel_hi:[1,0]
	v_pk_add_f32 v[28:29], v[28:29], 1.0 op_sel_hi:[1,0]
	v_pk_add_f32 v[30:31], v[30:31], 1.0 op_sel_hi:[1,0]
	v_pk_mul_f32 v[18:19], v[216:217], v[18:19]
	v_pk_mul_f32 v[16:17], v[218:219], v[16:17]
	v_rcp_f32_e32 v28, v28
	v_rcp_f32_e32 v29, v29
	v_rcp_f32_e32 v30, v30
	v_rcp_f32_e32 v31, v31
	v_pk_mul_f32 v[24:25], v[24:25], v[28:29]
	v_pk_mul_f32 v[26:27], v[26:27], v[30:31]
	v_pk_mul_f32 v[18:19], v[24:25], v[18:19]
	v_pk_mul_f32 v[16:17], v[26:27], v[16:17]
	v_cvt_pk_bf16_f32 v40, v18, v19
	v_cvt_pk_bf16_f32 v41, v16, v17
	global_store_dwordx2 v[2:3], v[40:41], off offset:128
	v_lshlrev_b32_e32 v32, 16, v194
	v_and_b32_e32 v33, 0xffff0000, v194
	v_lshlrev_b32_e32 v34, 16, v195
	v_and_b32_e32 v35, 0xffff0000, v195
	v_mul_f32_e32 v36, 0xbfb8aa3b, v32
	v_mul_f32_e32 v37, 0xbfb8aa3b, v33
	v_mul_f32_e32 v38, 0xbfb8aa3b, v34
	v_mul_f32_e32 v39, 0xbfb8aa3b, v35
	v_exp_f32_e32 v36, v36
	v_exp_f32_e32 v37, v37
	v_exp_f32_e32 v38, v38
	v_exp_f32_e32 v39, v39
	v_pk_mul_f32 v[14:15], v[14:15], v[6:7] op_sel_hi:[1,0]
	v_pk_mul_f32 v[12:13], v[12:13], v[6:7] op_sel_hi:[1,0]
	v_pk_add_f32 v[36:37], v[36:37], 1.0 op_sel_hi:[1,0]
	v_pk_add_f32 v[38:39], v[38:39], 1.0 op_sel_hi:[1,0]
	v_pk_mul_f32 v[14:15], v[220:221], v[14:15]
	v_pk_mul_f32 v[12:13], v[222:223], v[12:13]
	v_rcp_f32_e32 v36, v36
	v_rcp_f32_e32 v37, v37
	v_rcp_f32_e32 v38, v38
	v_rcp_f32_e32 v39, v39
	v_pk_mul_f32 v[32:33], v[32:33], v[36:37]
	v_pk_mul_f32 v[34:35], v[34:35], v[38:39]
	v_pk_mul_f32 v[14:15], v[32:33], v[14:15]
	v_pk_mul_f32 v[12:13], v[34:35], v[12:13]
	v_cvt_pk_bf16_f32 v44, v14, v15
	v_cvt_pk_bf16_f32 v45, v12, v13
	global_store_dwordx2 v[2:3], v[44:45], off offset:160
	v_lshlrev_b32_e32 v24, 16, v196
	v_and_b32_e32 v25, 0xffff0000, v196
	v_lshlrev_b32_e32 v26, 16, v197
	v_and_b32_e32 v27, 0xffff0000, v197
	v_mul_f32_e32 v28, 0xbfb8aa3b, v24
	v_mul_f32_e32 v29, 0xbfb8aa3b, v25
	v_mul_f32_e32 v30, 0xbfb8aa3b, v26
	v_mul_f32_e32 v31, 0xbfb8aa3b, v27
	v_exp_f32_e32 v28, v28
	v_exp_f32_e32 v29, v29
	v_exp_f32_e32 v30, v30
	v_exp_f32_e32 v31, v31
	v_pk_mul_f32 v[10:11], v[10:11], v[6:7] op_sel_hi:[1,0]
	v_pk_mul_f32 v[8:9], v[8:9], v[6:7] op_sel_hi:[1,0]
	v_pk_add_f32 v[28:29], v[28:29], 1.0 op_sel_hi:[1,0]
	v_pk_add_f32 v[30:31], v[30:31], 1.0 op_sel_hi:[1,0]
	v_pk_mul_f32 v[10:11], v[224:225], v[10:11]
	v_pk_mul_f32 v[8:9], v[226:227], v[8:9]
	v_rcp_f32_e32 v28, v28
	v_rcp_f32_e32 v29, v29
	v_rcp_f32_e32 v30, v30
	v_rcp_f32_e32 v31, v31
	v_pk_mul_f32 v[24:25], v[24:25], v[28:29]
	v_pk_mul_f32 v[26:27], v[26:27], v[30:31]
	v_pk_mul_f32 v[10:11], v[24:25], v[10:11]
	v_pk_mul_f32 v[8:9], v[26:27], v[8:9]
	v_cvt_pk_bf16_f32 v40, v10, v11
	v_cvt_pk_bf16_f32 v41, v8, v9
	global_store_dwordx2 v[2:3], v[40:41], off offset:192
	v_lshlrev_b32_e32 v32, 16, v198
	v_and_b32_e32 v33, 0xffff0000, v198
	v_lshlrev_b32_e32 v34, 16, v199
	v_and_b32_e32 v35, 0xffff0000, v199
	v_mul_f32_e32 v36, 0xbfb8aa3b, v32
	v_mul_f32_e32 v37, 0xbfb8aa3b, v33
	v_mul_f32_e32 v38, 0xbfb8aa3b, v34
	v_mul_f32_e32 v39, 0xbfb8aa3b, v35
	v_exp_f32_e32 v36, v36
	v_exp_f32_e32 v37, v37
	v_exp_f32_e32 v38, v38
	v_exp_f32_e32 v39, v39
	v_pk_mul_f32 v[4:5], v[4:5], v[6:7] op_sel_hi:[1,0]
	v_pk_mul_f32 v[0:1], v[0:1], v[6:7] op_sel_hi:[1,0]
	v_pk_add_f32 v[36:37], v[36:37], 1.0 op_sel_hi:[1,0]
	v_pk_add_f32 v[38:39], v[38:39], 1.0 op_sel_hi:[1,0]
	v_pk_mul_f32 v[4:5], v[228:229], v[4:5]
	v_pk_mul_f32 v[0:1], v[230:231], v[0:1]
	v_rcp_f32_e32 v36, v36
	v_rcp_f32_e32 v37, v37
	v_rcp_f32_e32 v38, v38
	v_rcp_f32_e32 v39, v39
	v_pk_mul_f32 v[32:33], v[32:33], v[36:37]
	v_pk_mul_f32 v[34:35], v[34:35], v[38:39]
	v_pk_mul_f32 v[4:5], v[32:33], v[4:5]
	v_pk_mul_f32 v[0:1], v[34:35], v[0:1]
	v_cvt_pk_bf16_f32 v44, v4, v5
	v_cvt_pk_bf16_f32 v45, v0, v1
	global_store_dwordx2 v[2:3], v[44:45], off offset:224
	s_waitcnt lgkmcnt(0)
	s_barrier
	s_cbranch_scc1 .LBB0_495
